# phase-0 expert-table quantisation loop: g_ffn loads hoisted out of the loop and two-row-deep prefetch (alternating register sets)
# baseline (speedup 1.0000x reference)
.LBB0_113:
	s_barrier
	s_load_dword s0, s[14:15], 0x10
	s_load_dword s2, s[14:15], 0x0
	v_ashrrev_i32_e32 v1, 6, v130
	v_lshl_add_u32 v162, s60, 2, v1
	v_and_b32_e32 v132, 63, v130
	s_waitcnt lgkmcnt(0)
	s_lshr_b32 s0, s0, 16
	s_cmp_lg_u32 s0, 0
	s_cselect_b64 s[0:1], -1, 0
	s_cmp_lg_u64 s[0:1], 0
	s_addc_u32 s4, s2, 0
	s_mov_b32 s0, 0x8000
	s_lshl_b32 s2, s4, 2
	v_cmp_gt_i32_e32 vcc, s0, v162
	s_and_saveexec_b64 s[6:7], vcc
	s_cbranch_execz .LBB0_126
	v_readlane_b32 s16, v254, 32
	v_readlane_b32 s36, v254, 16
	s_movk_i32 s3, 0x4000
	v_readlane_b32 s17, v254, 33
	v_readlane_b32 s51, v254, 31
	v_readlane_b32 s50, v254, 30
	v_mov_b32_e32 v1, s17
	v_mov_b32_e32 v2, s51
	v_cmp_gt_i32_e32 vcc, s3, v162
	v_mov_b32_e32 v35, 0
	v_readlane_b32 s44, v254, 24
	v_cndmask_b32_e32 v3, v1, v2, vcc
	v_mov_b32_e32 v1, s16
	v_mov_b32_e32 v2, s50
	v_cndmask_b32_e32 v2, v1, v2, vcc
	v_lshlrev_b32_e32 v1, 12, v162
	v_and_b32_e32 v34, 0x3fff000, v1
	v_lshl_add_u64 v[2:3], v[2:3], 0, v[34:35]
	v_lshlrev_b32_e32 v34, 6, v132
	v_lshl_add_u64 v[18:19], v[2:3], 0, v[34:35]
	global_load_dwordx4 v[14:17], v[18:19], off
	global_load_dwordx4 v[10:13], v[18:19], off offset:16
	global_load_dwordx4 v[2:5], v[18:19], off offset:32
	global_load_dwordx4 v[6:9], v[18:19], off offset:48
	v_mbcnt_lo_u32_b32 v1, -1, 0
	v_mbcnt_hi_u32_b32 v19, -1, v1
	v_and_b32_e32 v1, 64, v19
	v_add_u32_e32 v20, 64, v1
	v_xor_b32_e32 v1, 32, v19
	v_cmp_lt_i32_e32 vcc, v1, v20
	v_xor_b32_e32 v21, 16, v19
	v_readlane_b32 s45, v254, 25
	v_cndmask_b32_e32 v1, v19, v1, vcc
	v_cmp_lt_i32_e32 vcc, v21, v20
	v_lshlrev_b32_e32 v18, 2, v132
	s_add_u32 s8, s92, 0x30000000
	v_cndmask_b32_e32 v21, v19, v21, vcc
	v_lshlrev_b32_e32 v46, 2, v21
	v_xor_b32_e32 v21, 8, v19
	v_cmp_lt_i32_e32 vcc, v21, v20
	v_cmp_eq_u32_e64 s[0:1], 0, v132
	v_lshlrev_b32_e32 v1, 2, v1
	v_cndmask_b32_e32 v21, v19, v21, vcc
	v_lshlrev_b32_e32 v47, 2, v21
	v_xor_b32_e32 v21, 4, v19
	v_cmp_lt_i32_e32 vcc, v21, v20
	s_addc_u32 s9, s93, 0
	v_lshl_add_u64 v[36:37], s[44:45], 0, v[34:35]
	v_cndmask_b32_e32 v21, v19, v21, vcc
	v_lshlrev_b32_e32 v48, 2, v21
	v_xor_b32_e32 v21, 2, v19
	v_cmp_lt_i32_e32 vcc, v21, v20
	s_mov_b64 s[10:11], 0
	s_movk_i32 s5, 0x7fff
	v_cndmask_b32_e32 v21, v19, v21, vcc
	v_lshlrev_b32_e32 v49, 2, v21
	v_xor_b32_e32 v21, 1, v19
	v_cmp_lt_i32_e32 vcc, v21, v20
	v_mov_b32_e32 v51, s17
	v_mov_b32_e32 v52, s51
	v_cndmask_b32_e32 v19, v19, v21, vcc
	v_lshlrev_b32_e32 v50, 2, v19
	v_mov_b32_e32 v53, s16
	v_mov_b32_e32 v54, s50
	v_lshlrev_b32_e32 v38, 4, v18
	v_mov_b32_e32 v39, v35
	s_mov_b32 s16, 0xda24260
	s_mov_b32 s17, 0x42fe0000
	v_lshlrev_b32_e32 v40, 4, v132
	v_mov_b32_e32 v41, v162
	v_readlane_b32 s18, v254, 34
	v_readlane_b32 s19, v254, 35
	v_readlane_b32 s37, v254, 17
	v_readlane_b32 s38, v254, 18
	v_readlane_b32 s39, v254, 19
	v_readlane_b32 s40, v254, 20
	v_readlane_b32 s41, v254, 21
	v_readlane_b32 s42, v254, 22
	v_readlane_b32 s43, v254, 23
	v_readlane_b32 s46, v254, 26
	v_readlane_b32 s47, v254, 27
	v_readlane_b32 s48, v254, 28
	v_readlane_b32 s49, v254, 29
	v_add_u32_e32 v247, s2, v41
	v_min_i32_e32 v246, 0x7fff, v247
	v_cmp_gt_i32_e32 vcc, s3, v247
	v_lshlrev_b32_e32 v246, 12, v246
	v_and_b32_e32 v34, 0x3fff000, v246
	v_cndmask_b32_e32 v249, v51, v52, vcc
	v_cndmask_b32_e32 v248, v53, v54, vcc
	v_lshl_add_u64 v[248:249], v[248:249], 0, v[34:35]
	v_lshl_add_u64 v[42:43], v[248:249], 0, v[38:39]
	global_load_dwordx4 v[18:21], v[42:43], off offset:48
	global_load_dwordx4 v[22:25], v[42:43], off offset:32
	global_load_dwordx4 v[26:29], v[42:43], off offset:16
	global_load_dwordx4 v[30:33], v[42:43], off
	global_load_dwordx4 v[230:233], v[36:37], off
	global_load_dwordx4 v[234:237], v[36:37], off offset:16
	global_load_dwordx4 v[238:241], v[36:37], off offset:32
	global_load_dwordx4 v[242:245], v[36:37], off offset:48
	s_waitcnt vmcnt(0)
	s_mov_b32 s61, 0
	s_branch .LBB0_116
.LBB0_115:
	s_or_b64 exec, exec, s[12:13]
	v_cmp_lt_i32_e32 vcc, s5, v55
	s_or_b64 s[10:11], vcc, s[10:11]
	v_mov_b32_e32 v41, v55
	s_waitcnt vmcnt(6)
	s_cmp_eq_u32 s61, 0
	s_cbranch_scc0 .Lp0e_cpy
	v_mov_b32_e32 v14, v30
	v_mov_b32_e32 v15, v31
	v_mov_b32_e32 v16, v32
	v_mov_b32_e32 v17, v33
	v_mov_b32_e32 v10, v26
	v_mov_b32_e32 v11, v27
	v_mov_b32_e32 v12, v28
	v_mov_b32_e32 v13, v29
	v_mov_b32_e32 v2, v22
	v_mov_b32_e32 v3, v23
	v_mov_b32_e32 v4, v24
	v_mov_b32_e32 v5, v25
	v_mov_b32_e32 v6, v18
	v_mov_b32_e32 v7, v19
	v_mov_b32_e32 v8, v20
	v_mov_b32_e32 v9, v21
	s_branch .Lp0e_cpd
.Lp0e_cpy:
	v_mov_b32_e32 v14, v224
	v_mov_b32_e32 v15, v225
	v_mov_b32_e32 v16, v226
	v_mov_b32_e32 v17, v227
	v_mov_b32_e32 v10, v220
	v_mov_b32_e32 v11, v221
	v_mov_b32_e32 v12, v222
	v_mov_b32_e32 v13, v223
	v_mov_b32_e32 v2, v216
	v_mov_b32_e32 v3, v217
	v_mov_b32_e32 v4, v218
	v_mov_b32_e32 v5, v219
	v_mov_b32_e32 v6, v212
	v_mov_b32_e32 v7, v213
	v_mov_b32_e32 v8, v214
	v_mov_b32_e32 v9, v215
.Lp0e_cpd:
	s_xor_b32 s61, s61, 1
	s_andn2_b64 exec, exec, s[10:11]
	s_cbranch_execz .LBB0_126
.LBB0_116:
	v_add_u32_e32 v55, s2, v41
	v_add_u32_e32 v247, s2, v55
	v_min_i32_e32 v246, 0x7fff, v247
	v_cmp_gt_i32_e32 vcc, s3, v247
	v_lshlrev_b32_e32 v246, 12, v246
	v_and_b32_e32 v34, 0x3fff000, v246
	v_cndmask_b32_e32 v249, v51, v52, vcc
	v_cndmask_b32_e32 v248, v53, v54, vcc
	v_lshl_add_u64 v[248:249], v[248:249], 0, v[34:35]
	v_lshl_add_u64 v[42:43], v[248:249], 0, v[38:39]
	s_cmp_eq_u32 s61, 0
	s_cbranch_scc0 .Lp0e_ldx
	global_load_dwordx4 v[212:215], v[42:43], off offset:48
	global_load_dwordx4 v[216:219], v[42:43], off offset:32
	global_load_dwordx4 v[220:223], v[42:43], off offset:16
	global_load_dwordx4 v[224:227], v[42:43], off
	s_branch .Lp0e_ldd
.Lp0e_ldx:
	global_load_dwordx4 v[18:21], v[42:43], off offset:48
	global_load_dwordx4 v[22:25], v[42:43], off offset:32
	global_load_dwordx4 v[26:29], v[42:43], off offset:16
	global_load_dwordx4 v[30:33], v[42:43], off
.Lp0e_ldd:
	v_cmp_gt_i32_e32 vcc, s3, v41
	s_and_saveexec_b64 s[12:13], vcc
	s_cbranch_execnz .LBB0_124
	s_or_b64 exec, exec, s[12:13]
	s_and_saveexec_b64 s[12:13], vcc
	s_cbranch_execnz .LBB0_125

.LBB0_119:
	v_mov_b32_e32 v42, v238
	v_mov_b32_e32 v43, v239
	v_mov_b32_e32 v44, v240
	v_mov_b32_e32 v45, v241
	v_pk_mul_f32 v[4:5], v[4:5], v[44:45]
	v_pk_mul_f32 v[2:3], v[2:3], v[42:43]
.LBB0_120:
	s_or_b64 exec, exec, s[12:13]
	v_mov_b32_e32 v34, 0x43000000
	v_mov_b64_e32 v[44:45], 64
	v_mov_b64_e32 v[42:43], 0x36f20000
	s_and_saveexec_b64 s[12:13], vcc
	s_cbranch_execz .LBB0_122
	v_mov_b32_e32 v56, v242
	v_mov_b32_e32 v57, v243
	v_mov_b32_e32 v58, v244
	v_mov_b32_e32 v59, v245
	v_mov_b32_e32 v34, 0
	v_mov_b64_e32 v[44:45], 0
	v_mov_b64_e32 v[42:43], 0x36f10000
	v_pk_mul_f32 v[8:9], v[8:9], v[58:59]
	v_pk_mul_f32 v[6:7], v[6:7], v[56:57]
.LBB0_122:
	s_or_b64 exec, exec, s[12:13]
	v_max_f32_e64 v45, |v17|, |v17|
	v_max_f32_e64 v56, |v16|, |v16|
	v_max_f32_e32 v45, v56, v45
	v_max_f32_e64 v56, |v13|, |v13|
	v_max_f32_e64 v57, |v12|, |v12|
	v_max_f32_e32 v56, v57, v56
	v_max3_f32 v45, |v14|, |v15|, v45
	v_max3_f32 v56, |v10|, |v11|, v56
	v_max3_f32 v45, v45, 0, v56
	v_max_f32_e64 v56, |v5|, |v5|
	v_max_f32_e64 v57, |v4|, |v4|
	v_max_f32_e32 v56, v57, v56
	v_max_f32_e64 v57, |v9|, |v9|
	v_max_f32_e64 v58, |v8|, |v8|
	v_max_f32_e32 v57, v58, v57
	v_max3_f32 v56, |v2|, |v3|, v56
	v_max3_f32 v57, |v6|, |v7|, v57
	v_max3_f32 v45, v45, v56, v57
	ds_bpermute_b32 v56, v1, v45
	s_waitcnt lgkmcnt(0)
	v_max_f32_e32 v56, v56, v56
	v_max_f32_e32 v45, v45, v56
	ds_bpermute_b32 v56, v46, v45
	s_waitcnt lgkmcnt(0)
	v_max_f32_e32 v56, v56, v56
	v_max_f32_e32 v45, v45, v56
	ds_bpermute_b32 v56, v47, v45
	s_waitcnt lgkmcnt(0)
	v_max_f32_e32 v56, v56, v56
	v_max_f32_e32 v45, v45, v56
	ds_bpermute_b32 v56, v48, v45
	s_waitcnt lgkmcnt(0)
	v_max_f32_e32 v56, v56, v56
	v_max_f32_e32 v45, v45, v56
	ds_bpermute_b32 v56, v49, v45
	s_waitcnt lgkmcnt(0)
	v_max_f32_e32 v56, v56, v56
	v_max_f32_e32 v45, v45, v56
	ds_bpermute_b32 v56, v50, v45
	s_waitcnt lgkmcnt(0)
	v_max3_f32 v45, v45, v56, s16
	v_div_scale_f32 v56, s[12:13], v45, v45, s17
	v_rcp_f32_e32 v57, v56
	v_div_scale_f32 v58, vcc, s17, v45, s17
	v_fma_f32 v59, -v56, v57, 1.0
	v_fmac_f32_e32 v57, v59, v57
	v_mul_f32_e32 v59, v58, v57
	v_fma_f32 v60, -v56, v59, v58
	v_fmac_f32_e32 v59, v60, v57
	v_fma_f32 v56, -v56, v59, v58
	v_div_fmas_f32 v56, v56, v57, v59
	v_div_fixup_f32 v58, v56, v45, s17
	v_mul_f32_e32 v14, v14, v58
	v_mul_f32_e32 v57, v10, v58
	v_mul_f32_e32 v15, v15, v58
	v_mul_f32_e32 v17, v17, v58
	v_mul_f32_e32 v59, v11, v58
	v_rndne_f32_e32 v10, v14
	v_rndne_f32_e32 v11, v57
	v_mul_f32_e32 v12, v12, v58
	v_mul_f32_e32 v16, v16, v58
	v_rndne_f32_e32 v14, v15
	v_rndne_f32_e32 v56, v17
	v_rndne_f32_e32 v15, v59
	v_rndne_f32_e32 v17, v12
	v_mul_f32_e32 v12, v13, v58
	v_pk_add_f32 v[10:11], v[34:35], v[10:11] op_sel_hi:[0,1]
	v_rndne_f32_e32 v16, v16
	v_rndne_f32_e32 v57, v12
	v_cvt_i32_f32_e32 v12, v11
	v_cvt_i32_f32_e32 v13, v10
	v_pk_add_f32 v[10:11], v[34:35], v[14:15] op_sel_hi:[0,1]
	v_cvt_i32_f32_e32 v14, v10
	v_cvt_i32_f32_e32 v15, v11
	v_pk_add_f32 v[10:11], v[34:35], v[16:17] op_sel_hi:[0,1]
	v_cvt_i32_f32_sdwa v16, v10 dst_sel:WORD_1 dst_unused:UNUSED_PAD src0_sel:DWORD
	v_cvt_i32_f32_sdwa v17, v11 dst_sel:WORD_1 dst_unused:UNUSED_PAD src0_sel:DWORD
	v_pk_add_f32 v[10:11], v[34:35], v[56:57] op_sel_hi:[0,1]
	v_cvt_i32_f32_sdwa v11, v11 dst_sel:BYTE_3 dst_unused:UNUSED_PAD src0_sel:DWORD
	v_cvt_i32_f32_sdwa v10, v10 dst_sel:BYTE_3 dst_unused:UNUSED_PAD src0_sel:DWORD
	v_mul_f32_e32 v3, v3, v58
	v_lshlrev_b32_e32 v14, 8, v14
	v_or_b32_sdwa v11, v11, v12 dst_sel:DWORD dst_unused:UNUSED_PAD src0_sel:DWORD src1_sel:BYTE_0
	v_rndne_f32_e32 v12, v3
	v_mul_f32_e32 v3, v4, v58
	v_and_b32_e32 v14, 0xff00, v14
	v_or_b32_sdwa v10, v10, v13 dst_sel:DWORD dst_unused:UNUSED_PAD src0_sel:DWORD src1_sel:BYTE_0
	v_rndne_f32_e32 v4, v3
	v_mul_f32_e32 v3, v5, v58
	v_or_b32_e32 v10, v10, v14
	v_mul_f32_e32 v2, v2, v58
	v_rndne_f32_e32 v14, v3
	v_mul_f32_e32 v3, v6, v58
	v_lshlrev_b32_e32 v15, 8, v15
	v_rndne_f32_e32 v2, v2
	v_rndne_f32_e32 v3, v3
	v_mul_f32_e32 v5, v7, v58
	v_and_b32_e32 v15, 0xff00, v15
	v_rndne_f32_e32 v13, v5
	v_mul_f32_e32 v5, v8, v58
	v_mul_f32_e32 v6, v9, v58
	v_pk_add_f32 v[2:3], v[34:35], v[2:3] op_sel_hi:[0,1]
	v_or_b32_e32 v11, v11, v15
	v_rndne_f32_e32 v5, v5
	v_rndne_f32_e32 v15, v6
	v_cvt_i32_f32_e32 v6, v3
	v_cvt_i32_f32_e32 v7, v2
	v_pk_add_f32 v[2:3], v[34:35], v[12:13] op_sel_hi:[0,1]
	v_cvt_i32_f32_e32 v8, v2
	v_cvt_i32_f32_e32 v9, v3
	v_pk_add_f32 v[2:3], v[34:35], v[4:5] op_sel_hi:[0,1]
	v_cvt_i32_f32_sdwa v4, v2 dst_sel:WORD_1 dst_unused:UNUSED_PAD src0_sel:DWORD
	v_cvt_i32_f32_sdwa v5, v3 dst_sel:WORD_1 dst_unused:UNUSED_PAD src0_sel:DWORD
	v_pk_add_f32 v[2:3], v[34:35], v[14:15] op_sel_hi:[0,1]
	v_cvt_i32_f32_sdwa v2, v2 dst_sel:BYTE_3 dst_unused:UNUSED_PAD src0_sel:DWORD
	v_cvt_i32_f32_sdwa v3, v3 dst_sel:BYTE_3 dst_unused:UNUSED_PAD src0_sel:DWORD
	v_lshlrev_b32_e32 v8, 8, v8
	v_and_b32_e32 v8, 0xff00, v8
	v_or_b32_sdwa v2, v2, v7 dst_sel:DWORD dst_unused:UNUSED_PAD src0_sel:DWORD src1_sel:BYTE_0
	v_lshlrev_b32_e32 v9, 8, v9
	v_and_b32_e32 v4, 0xff0000, v4
	v_or_b32_e32 v2, v2, v8
	v_and_b32_e32 v9, 0xff00, v9
	v_or_b32_sdwa v3, v3, v6 dst_sel:DWORD dst_unused:UNUSED_PAD src0_sel:DWORD src1_sel:BYTE_0
	v_or_b32_e32 v12, v2, v4
	v_and_b32_e32 v2, 0x3fff, v41
	v_and_b32_e32 v5, 0xff0000, v5
	v_or_b32_e32 v3, v3, v9
	v_lshlrev_b32_e32 v34, 11, v2
	v_or_b32_e32 v13, v3, v5
	v_lshl_add_u64 v[4:5], s[8:9], 0, v[34:35]
	v_lshlrev_b32_e32 v34, 4, v44
	v_and_b32_e32 v17, 0xff0000, v17
	v_and_b32_e32 v16, 0xff0000, v16
	v_lshl_add_u64 v[4:5], v[4:5], 0, v[34:35]
	v_mov_b32_e32 v41, v35
	v_or_b32_e32 v11, v11, v17
	v_or_b32_e32 v10, v10, v16
	v_lshl_add_u64 v[4:5], v[4:5], 0, v[40:41]
	global_store_dwordx4 v[4:5], v[10:13], off
	s_and_saveexec_b64 s[12:13], s[0:1]
	s_cbranch_execz .LBB0_115
	v_lshl_add_u64 v[4:5], s[92:93], 0, v[42:43]
	v_lshlrev_b32_e32 v34, 2, v2
	v_lshl_add_u64 v[2:3], v[4:5], 0, v[34:35]
	v_mul_f32_e32 v4, 0x3c010204, v45
	global_store_dword v[2:3], v4, off
	s_branch .LBB0_115
.LBB0_124:
	v_mov_b32_e32 v42, v230
	v_mov_b32_e32 v43, v231
	v_mov_b32_e32 v44, v232
	v_mov_b32_e32 v45, v233
	v_pk_mul_f32 v[16:17], v[16:17], v[44:45]
	v_pk_mul_f32 v[14:15], v[14:15], v[42:43]
	s_or_b64 exec, exec, s[12:13]
	s_and_saveexec_b64 s[12:13], vcc
	s_cbranch_execz .LBB0_118
.LBB0_125:
	v_mov_b32_e32 v42, v234
	v_mov_b32_e32 v43, v235
	v_mov_b32_e32 v44, v236
	v_mov_b32_e32 v45, v237
	v_pk_mul_f32 v[12:13], v[12:13], v[44:45]
	v_pk_mul_f32 v[10:11], v[10:11], v[42:43]
	s_or_b64 exec, exec, s[12:13]
	s_and_saveexec_b64 s[12:13], vcc
	s_cbranch_execnz .LBB0_119
	s_branch .LBB0_120
.LBB0_126:
	s_waitcnt vmcnt(0)
	s_or_b64 exec, exec, s[6:7]
	s_mov_b32 s61, 0
	s_lshl_b64 s[0:1], s[60:61], 8
	v_ashrrev_i32_e32 v131, 31, v130
	v_lshl_add_u64 v[2:3], s[0:1], 0, v[130:131]
	s_mov_b64 s[0:1], 0x8000
	v_cmp_gt_u64_e32 vcc, s[0:1], v[2:3]
	s_and_saveexec_b64 s[0:1], vcc
	s_cbranch_execz .LBB0_129
	s_mov_b32 s5, s61
	s_lshl_b64 s[6:7], s[4:5], 8
	s_add_u32 s8, s92, 0x34a00000
	v_readlane_b32 s16, v254, 16
	s_addc_u32 s9, s93, 0
	s_lshl_b64 s[10:11], s[60:61], 12
	v_readlane_b32 s28, v254, 28
	v_readlane_b32 s17, v254, 17
	v_readlane_b32 s29, v254, 29
	s_add_u32 s10, s28, s10
	v_readlane_b32 s18, v254, 18
	v_readlane_b32 s19, v254, 19
	s_addc_u32 s11, s29, s11
	s_lshl_b64 s[12:13], s[60:61], 11
	s_lshl_b64 s[16:17], s[60:61], 10
	v_lshl_add_u64 v[4:5], v[130:131], 4, s[10:11]
	s_lshl_b64 s[10:11], s[4:5], 12
	v_lshl_add_u64 v[6:7], v[130:131], 3, s[12:13]
	s_lshl_b64 s[12:13], s[4:5], 11
	v_lshl_add_u64 v[8:9], v[130:131], 2, s[16:17]
	s_lshl_b64 s[4:5], s[4:5], 10
	s_mov_b64 s[16:17], 0
	s_movk_i32 s3, 0x3f80
	v_mov_b32_e32 v11, 0
	s_mov_b64 s[18:19], 0x7fff
	v_readlane_b32 s20, v254, 20
	v_readlane_b32 s21, v254, 21
	v_readlane_b32 s22, v254, 22
	v_readlane_b32 s23, v254, 23
	v_readlane_b32 s24, v254, 24
	v_readlane_b32 s25, v254, 25
	v_readlane_b32 s26, v254, 26
	v_readlane_b32 s27, v254, 27
	v_readlane_b32 s30, v254, 30
	v_readlane_b32 s31, v254, 31
